# selection slow-path pairs: 32 bias LUT lookups batched (was 32 serialized exec-masked LDS round trips)
# speedup vs baseline: 1.0171x; 1.0067x over previous
; __device__ __forceinline__ void nsa_unit(const Params& p, int bg, int jq, LAS unsigned char* lds, int wave, int lane, bool build_lut) {
;     ...
;                     float mx = NEG_INF;
; #pragma unroll
;                     for (int u = 0; u < 2; ++u)
; #pragma unroll
;                         for (int kt = 0; kt < 4; ++kt)
; #pragma unroll
;                             for (int e = 0; e < 4; ++e) {
;                                 const int d = tqg - 64 * nb[u] - 16 * kt - 4 * fq - e;
;                                 const bool okk = ok[u] && d >= 0;
;                                 const float v = okk ? (sc[u][kt][e] + lutr16[min(max(d, 0), 128)]) : NEG_INF;
;                                 sc[u][kt][e] = v; mx = fmaxf(mx, v);
.LBB0_1204:
	s_andn2_b64 vcc, exec, s[24:25]
	s_mov_b64 s[24:25], -1
	s_cbranch_vccnz .Lsel_fast
	s_lshl_b32 s9, s22, 6
	s_sub_i32 s9, 0, s9
	s_lshl_b32 s8, s8, 6
	s_sub_i32 s8, 0, s8
	v_mov_b32_e32 v240, 0xff800000
	v_add_u32_e32 v2, s9, v168
	v_min_u32_e32 v2, 0x80, v2
	v_lshl_add_u32 v2, v2, 2, v231
	ds_read_b32 v2, v2 offset:8448
	v_add_u32_e32 v1, s9, v169
	v_min_u32_e32 v1, 0x80, v1
	v_lshl_add_u32 v1, v1, 2, v231
	ds_read_b32 v1, v1 offset:8448
	v_add_u32_e32 v180, s9, v170
	v_min_u32_e32 v180, 0x80, v180
	v_lshl_add_u32 v180, v180, 2, v231
	ds_read_b32 v180, v180 offset:8448
	v_add_u32_e32 v3, s9, v171
	v_min_u32_e32 v3, 0x80, v3
	v_lshl_add_u32 v3, v3, 2, v231
	ds_read_b32 v3, v3 offset:8448
	v_add_u32_e32 v193, s9, v172
	v_min_u32_e32 v193, 0x80, v193
	v_lshl_add_u32 v193, v193, 2, v231
	ds_read_b32 v193, v193 offset:8448
	v_add_u32_e32 v192, s9, v173
	v_min_u32_e32 v192, 0x80, v192
	v_lshl_add_u32 v192, v192, 2, v231
	ds_read_b32 v192, v192 offset:8448
	v_add_u32_e32 v195, s9, v174
	v_min_u32_e32 v195, 0x80, v195
	v_lshl_add_u32 v195, v195, 2, v231
	ds_read_b32 v195, v195 offset:8448
	v_add_u32_e32 v194, s9, v175
	v_min_u32_e32 v194, 0x80, v194
	v_lshl_add_u32 v194, v194, 2, v231
	ds_read_b32 v194, v194 offset:8448
	v_add_u32_e32 v197, s9, v176
	v_min_u32_e32 v197, 0x80, v197
	v_lshl_add_u32 v197, v197, 2, v231
	ds_read_b32 v197, v197 offset:8448
	v_add_u32_e32 v196, s9, v185
	v_min_u32_e32 v196, 0x80, v196
	v_lshl_add_u32 v196, v196, 2, v231
	ds_read_b32 v196, v196 offset:8448
	v_add_u32_e32 v199, s9, v186
	v_min_u32_e32 v199, 0x80, v199
	v_lshl_add_u32 v199, v199, 2, v231
	ds_read_b32 v199, v199 offset:8448
	v_add_u32_e32 v198, s9, v187
	v_min_u32_e32 v198, 0x80, v198
	v_lshl_add_u32 v198, v198, 2, v231
	ds_read_b32 v198, v198 offset:8448
	v_add_u32_e32 v201, s9, v188
	v_min_u32_e32 v201, 0x80, v201
	v_lshl_add_u32 v201, v201, 2, v231
	ds_read_b32 v201, v201 offset:8448
	v_add_u32_e32 v200, s9, v189
	v_min_u32_e32 v200, 0x80, v200
	v_lshl_add_u32 v200, v200, 2, v231
	ds_read_b32 v200, v200 offset:8448
	v_add_u32_e32 v203, s9, v190
	v_min_u32_e32 v203, 0x80, v203
	v_lshl_add_u32 v203, v203, 2, v231
	ds_read_b32 v203, v203 offset:8448
	v_add_u32_e32 v202, s9, v191
	v_min_u32_e32 v202, 0x80, v202
	v_lshl_add_u32 v202, v202, 2, v231
	ds_read_b32 v202, v202 offset:8448
	v_add_u32_e32 v206, s8, v168
	v_min_u32_e32 v206, 0x80, v206
	v_lshl_add_u32 v206, v206, 2, v231
	ds_read_b32 v206, v206 offset:8448
	v_add_u32_e32 v205, s8, v169
	v_min_u32_e32 v205, 0x80, v205
	v_lshl_add_u32 v205, v205, 2, v231
	ds_read_b32 v205, v205 offset:8448
	v_add_u32_e32 v208, s8, v170
	v_min_u32_e32 v208, 0x80, v208
	v_lshl_add_u32 v208, v208, 2, v231
	ds_read_b32 v208, v208 offset:8448
	v_add_u32_e32 v207, s8, v171
	v_min_u32_e32 v207, 0x80, v207
	v_lshl_add_u32 v207, v207, 2, v231
	ds_read_b32 v207, v207 offset:8448
	v_add_u32_e32 v211, s8, v172
	v_min_u32_e32 v211, 0x80, v211
	v_lshl_add_u32 v211, v211, 2, v231
	ds_read_b32 v211, v211 offset:8448
	v_add_u32_e32 v210, s8, v173
	v_min_u32_e32 v210, 0x80, v210
	v_lshl_add_u32 v210, v210, 2, v231
	ds_read_b32 v210, v210 offset:8448
	v_add_u32_e32 v216, s8, v174
	v_min_u32_e32 v216, 0x80, v216
	v_lshl_add_u32 v216, v216, 2, v231
	ds_read_b32 v216, v216 offset:8448
	v_add_u32_e32 v215, s8, v175
	v_min_u32_e32 v215, 0x80, v215
	v_lshl_add_u32 v215, v215, 2, v231
	ds_read_b32 v215, v215 offset:8448
	v_add_u32_e32 v218, s8, v176
	v_min_u32_e32 v218, 0x80, v218
	v_lshl_add_u32 v218, v218, 2, v231
	ds_read_b32 v218, v218 offset:8448
	v_add_u32_e32 v217, s8, v185
	v_min_u32_e32 v217, 0x80, v217
	v_lshl_add_u32 v217, v217, 2, v231
	ds_read_b32 v217, v217 offset:8448
	v_add_u32_e32 v220, s8, v186
	v_min_u32_e32 v220, 0x80, v220
	v_lshl_add_u32 v220, v220, 2, v231
	ds_read_b32 v220, v220 offset:8448
	v_add_u32_e32 v219, s8, v187
	v_min_u32_e32 v219, 0x80, v219
	v_lshl_add_u32 v219, v219, 2, v231
	ds_read_b32 v219, v219 offset:8448
	v_add_u32_e32 v232, s8, v188
	v_min_u32_e32 v232, 0x80, v232
	v_lshl_add_u32 v232, v232, 2, v231
	ds_read_b32 v232, v232 offset:8448
	v_add_u32_e32 v221, s8, v189
	v_min_u32_e32 v221, 0x80, v221
	v_lshl_add_u32 v221, v221, 2, v231
	ds_read_b32 v221, v221 offset:8448
	v_add_u32_e32 v234, s8, v190
	v_min_u32_e32 v234, 0x80, v234
	v_lshl_add_u32 v234, v234, 2, v231
	ds_read_b32 v234, v234 offset:8448
	v_add_u32_e32 v233, s8, v191
	v_min_u32_e32 v233, 0x80, v233
	v_lshl_add_u32 v233, v233, 2, v231
	ds_read_b32 v233, v233 offset:8448
	v_add_u32_e32 v238, s9, v168
	v_cmp_lt_i32_e32 vcc, -1, v238
	s_and_b64 vcc, vcc, s[6:7]
	v_add_u32_e32 v239, s9, v169
	s_waitcnt lgkmcnt(15)
; __device__ __forceinline__ float fast_exp2(float x) { return __builtin_amdgcn_exp2f(x); }
; __device__ __forceinline__ float xhalf_max(float x) { auto t = __builtin_amdgcn_permlane32_swap(__float_as_uint(x), __float_as_uint(x), false, false); return fmaxf(__uint_as_float(t[0]), __uint_as_float(t[1])); }
; __device__ __forceinline__ void nsa_unit(const Params& p, int bg, int jq, LAS unsigned char* lds, int wave, int lane, bool build_lut) {
;     ...
;                     float mx = NEG_INF;
; #pragma unroll
;                     for (int u = 0; u < 2; ++u)
; #pragma unroll
;                         for (int kt = 0; kt < 4; ++kt)
; #pragma unroll
;                             for (int e = 0; e < 4; ++e) {
;                                 const int d = tqg - 64 * nb[u] - 16 * kt - 4 * fq - e;
;                                 const bool okk = ok[u] && d >= 0;
;                                 const float v = okk ? (sc[u][kt][e] + lutr16[min(max(d, 0), 128)]) : NEG_INF;
;                                 sc[u][kt][e] = v; mx = fmaxf(mx, v);
;                             }
;                     { auto t1 = __builtin_amdgcn_permlane16_swap(__float_as_uint(mx), __float_as_uint(mx), false, false); mx = fmaxf(__uint_as_float(t1[0]), __uint_as_float(t1[1])); mx = xhalf_max(mx); }
;                     if (__any(mx > m + 2.0f)) {
;                         const float mnew = (mx > m + 2.0f) ? mx : m;
;                         const float alpha = fast_exp2(m - mnew);
;                         lacc = lacc * alpha; m = mnew;
; #pragma unroll
;                         for (int dt = 0; dt < 4; ++dt) o[dt] = o[dt] * alpha;
;                     }
	v_add_f32_e32 v2, v116, v2
	v_cndmask_b32_e32 v2, v240, v2, vcc
	v_cmp_lt_i32_e32 vcc, -1, v239
	s_and_b64 vcc, vcc, s[6:7]
	v_add_u32_e32 v238, s9, v170
	v_add_f32_e32 v1, v117, v1
	v_cndmask_b32_e32 v1, v240, v1, vcc
	v_cmp_lt_i32_e32 vcc, -1, v238
	s_and_b64 vcc, vcc, s[6:7]
	v_add_u32_e32 v239, s9, v171
	v_add_f32_e32 v180, v118, v180
	v_cndmask_b32_e32 v180, v240, v180, vcc
	v_cmp_lt_i32_e32 vcc, -1, v239
	s_and_b64 vcc, vcc, s[6:7]
	v_add_u32_e32 v238, s9, v172
	v_add_f32_e32 v3, v119, v3
	v_cndmask_b32_e32 v3, v240, v3, vcc
	v_cmp_lt_i32_e32 vcc, -1, v238
	s_and_b64 vcc, vcc, s[6:7]
	v_add_u32_e32 v239, s9, v173
	v_add_f32_e32 v193, v108, v193
	v_cndmask_b32_e32 v193, v240, v193, vcc
	v_cmp_lt_i32_e32 vcc, -1, v239
	s_and_b64 vcc, vcc, s[6:7]
	v_add_u32_e32 v238, s9, v174
	v_add_f32_e32 v192, v109, v192
	v_cndmask_b32_e32 v192, v240, v192, vcc
	v_cmp_lt_i32_e32 vcc, -1, v238
	s_and_b64 vcc, vcc, s[6:7]
	v_add_u32_e32 v239, s9, v175
	v_add_f32_e32 v195, v110, v195
	v_cndmask_b32_e32 v195, v240, v195, vcc
	v_cmp_lt_i32_e32 vcc, -1, v239
	s_and_b64 vcc, vcc, s[6:7]
	v_add_u32_e32 v238, s9, v176
	v_add_f32_e32 v194, v111, v194
	v_cndmask_b32_e32 v194, v240, v194, vcc
	v_cmp_lt_i32_e32 vcc, -1, v238
	s_and_b64 vcc, vcc, s[6:7]
	v_add_u32_e32 v239, s9, v185
	v_add_f32_e32 v197, v96, v197
	v_cndmask_b32_e32 v197, v240, v197, vcc
	v_cmp_lt_i32_e32 vcc, -1, v239
	s_and_b64 vcc, vcc, s[6:7]
	v_add_u32_e32 v238, s9, v186
	v_add_f32_e32 v196, v97, v196
	v_cndmask_b32_e32 v196, v240, v196, vcc
	v_cmp_lt_i32_e32 vcc, -1, v238
	s_and_b64 vcc, vcc, s[6:7]
	v_add_u32_e32 v239, s9, v187
	v_add_f32_e32 v199, v98, v199
	v_cndmask_b32_e32 v199, v240, v199, vcc
	v_cmp_lt_i32_e32 vcc, -1, v239
	s_and_b64 vcc, vcc, s[6:7]
	v_add_u32_e32 v238, s9, v188
	v_add_f32_e32 v198, v99, v198
	v_cndmask_b32_e32 v198, v240, v198, vcc
	v_cmp_lt_i32_e32 vcc, -1, v238
	s_and_b64 vcc, vcc, s[6:7]
	v_add_u32_e32 v239, s9, v189
	v_add_f32_e32 v201, v100, v201
	v_cndmask_b32_e32 v201, v240, v201, vcc
	v_cmp_lt_i32_e32 vcc, -1, v239
	s_and_b64 vcc, vcc, s[6:7]
	v_add_u32_e32 v238, s9, v190
	v_add_f32_e32 v200, v101, v200
	v_cndmask_b32_e32 v200, v240, v200, vcc
	v_cmp_lt_i32_e32 vcc, -1, v238
	s_and_b64 vcc, vcc, s[6:7]
	v_add_u32_e32 v239, s9, v191
	v_add_f32_e32 v203, v102, v203
	v_cndmask_b32_e32 v203, v240, v203, vcc
	v_cmp_lt_i32_e32 vcc, -1, v239
	s_and_b64 vcc, vcc, s[6:7]
	v_add_u32_e32 v238, s8, v168
	v_add_f32_e32 v202, v103, v202
	v_cndmask_b32_e32 v202, v240, v202, vcc
	v_cmp_lt_i32_e32 vcc, -1, v238
	s_and_b64 vcc, vcc, s[20:21]
	v_add_u32_e32 v239, s8, v169
	v_add_f32_e32 v206, v112, v206
	v_cndmask_b32_e32 v206, v240, v206, vcc
	v_cmp_lt_i32_e32 vcc, -1, v239
	s_and_b64 vcc, vcc, s[20:21]
	v_add_u32_e32 v238, s8, v170
	s_waitcnt lgkmcnt(14)
	v_add_f32_e32 v205, v113, v205
	v_cndmask_b32_e32 v205, v240, v205, vcc
	v_cmp_lt_i32_e32 vcc, -1, v238
	s_and_b64 vcc, vcc, s[20:21]
	v_add_u32_e32 v239, s8, v171
	s_waitcnt lgkmcnt(13)
	v_add_f32_e32 v208, v114, v208
	v_cndmask_b32_e32 v208, v240, v208, vcc
	v_cmp_lt_i32_e32 vcc, -1, v239
	s_and_b64 vcc, vcc, s[20:21]
	v_add_u32_e32 v238, s8, v172
	s_waitcnt lgkmcnt(12)
	v_add_f32_e32 v207, v115, v207
	v_cndmask_b32_e32 v207, v240, v207, vcc
	v_cmp_lt_i32_e32 vcc, -1, v238
	s_and_b64 vcc, vcc, s[20:21]
	v_add_u32_e32 v239, s8, v173
	s_waitcnt lgkmcnt(11)
	v_add_f32_e32 v211, v104, v211
	v_cndmask_b32_e32 v211, v240, v211, vcc
	v_cmp_lt_i32_e32 vcc, -1, v239
	s_and_b64 vcc, vcc, s[20:21]
	v_add_u32_e32 v238, s8, v174
	s_waitcnt lgkmcnt(10)
	v_add_f32_e32 v210, v105, v210
	v_cndmask_b32_e32 v210, v240, v210, vcc
	v_cmp_lt_i32_e32 vcc, -1, v238
	s_and_b64 vcc, vcc, s[20:21]
	v_add_u32_e32 v239, s8, v175
	s_waitcnt lgkmcnt(9)
	v_add_f32_e32 v216, v106, v216
	v_cndmask_b32_e32 v216, v240, v216, vcc
	v_cmp_lt_i32_e32 vcc, -1, v239
	s_and_b64 vcc, vcc, s[20:21]
	v_add_u32_e32 v238, s8, v176
	s_waitcnt lgkmcnt(8)
	v_add_f32_e32 v215, v107, v215
	v_cndmask_b32_e32 v215, v240, v215, vcc
	v_cmp_lt_i32_e32 vcc, -1, v238
	s_and_b64 vcc, vcc, s[20:21]
	v_add_u32_e32 v239, s8, v185
	s_waitcnt lgkmcnt(7)
	v_add_f32_e32 v218, v92, v218
	v_cndmask_b32_e32 v218, v240, v218, vcc
	v_cmp_lt_i32_e32 vcc, -1, v239
	s_and_b64 vcc, vcc, s[20:21]
	v_add_u32_e32 v238, s8, v186
	s_waitcnt lgkmcnt(6)
	v_add_f32_e32 v217, v93, v217
	v_cndmask_b32_e32 v217, v240, v217, vcc
	v_cmp_lt_i32_e32 vcc, -1, v238
	s_and_b64 vcc, vcc, s[20:21]
	v_add_u32_e32 v239, s8, v187
	s_waitcnt lgkmcnt(5)
	v_add_f32_e32 v220, v94, v220
	v_cndmask_b32_e32 v220, v240, v220, vcc
	v_cmp_lt_i32_e32 vcc, -1, v239
	s_and_b64 vcc, vcc, s[20:21]
	v_add_u32_e32 v238, s8, v188
	s_waitcnt lgkmcnt(4)
	v_add_f32_e32 v219, v95, v219
	v_cndmask_b32_e32 v219, v240, v219, vcc
	v_cmp_lt_i32_e32 vcc, -1, v238
	s_and_b64 vcc, vcc, s[20:21]
	v_add_u32_e32 v239, s8, v189
	s_waitcnt lgkmcnt(3)
	v_add_f32_e32 v232, v88, v232
	v_cndmask_b32_e32 v232, v240, v232, vcc
	v_cmp_lt_i32_e32 vcc, -1, v239
	s_and_b64 vcc, vcc, s[20:21]
	v_add_u32_e32 v238, s8, v190
	s_waitcnt lgkmcnt(2)
	v_add_f32_e32 v221, v89, v221
	v_cndmask_b32_e32 v221, v240, v221, vcc
	v_cmp_lt_i32_e32 vcc, -1, v238
	s_and_b64 vcc, vcc, s[20:21]
	v_add_u32_e32 v239, s8, v191
	s_waitcnt lgkmcnt(1)
	v_add_f32_e32 v234, v90, v234
	v_cndmask_b32_e32 v234, v240, v234, vcc
	v_cmp_lt_i32_e32 vcc, -1, v239
	s_and_b64 vcc, vcc, s[20:21]
	s_waitcnt lgkmcnt(0)
	v_add_f32_e32 v233, v91, v233
	v_cndmask_b32_e32 v233, v240, v233, vcc
	v_max3_f32 v120, v2, s81, v1
	v_max3_f32 v120, v120, v180, v3
	v_max3_f32 v120, v120, v193, v192
	v_max3_f32 v120, v120, v195, v194
	v_max3_f32 v120, v120, v197, v196
	v_max3_f32 v120, v120, v199, v198
	v_max3_f32 v120, v120, v201, v200
	v_max3_f32 v120, v120, v203, v202
	v_max3_f32 v120, v120, v206, v205
	v_max3_f32 v120, v120, v208, v207
	v_max3_f32 v120, v120, v211, v210
	v_max3_f32 v120, v120, v216, v215
	v_max3_f32 v120, v120, v218, v217
	v_max3_f32 v120, v120, v220, v219
	v_max3_f32 v120, v120, v232, v221
	v_max3_f32 v120, v120, v234, v233
	v_mov_b32_e32 v121, v120
	s_nop 1
	v_permlane16_swap_b32_e32 v120, v121
	v_max_f32_e32 v121, v121, v121
	v_max_f32_e32 v120, v120, v120
	v_max_f32_e32 v120, v120, v121
	v_mov_b32_e32 v121, v120
	s_nop 1
	v_permlane32_swap_b32_e32 v120, v121
	v_max_f32_e32 v121, v121, v121
	v_max_f32_e32 v120, v120, v120
	v_max_f32_e32 v209, v120, v121
	v_add_f32_e32 v120, 2.0, v157
	v_cmp_gt_f32_e32 vcc, v209, v120
	v_mov_b64_e32 v[138:139], v[26:27]
	v_mov_b64_e32 v[130:131], v[42:43]
	v_mov_b64_e32 v[126:127], v[46:47]
	v_mov_b64_e32 v[122:123], v[50:51]
	v_mov_b64_e32 v[134:135], v[54:55]
	v_mov_b64_e32 v[136:137], v[24:25]
	v_mov_b64_e32 v[128:129], v[40:41]
	v_mov_b64_e32 v[124:125], v[44:45]
	v_mov_b64_e32 v[120:121], v[48:49]
	v_mov_b64_e32 v[132:133], v[52:53]
	v_mov_b32_e32 v204, v157
	s_cbranch_vccz .LBB0_1271
; __device__ __forceinline__ float fast_exp2(float x) { return __builtin_amdgcn_exp2f(x); }
; __device__ __forceinline__ void nsa_unit(const Params& p, int bg, int jq, LAS unsigned char* lds, int wave, int lane, bool build_lut) {
;     ...
;                     if (__any(mx > m + 2.0f)) {
;                         const float mnew = (mx > m + 2.0f) ? mx : m;
;                         const float alpha = fast_exp2(m - mnew);
;                         lacc = lacc * alpha; m = mnew;
; #pragma unroll
;                         for (int dt = 0; dt < 4; ++dt) o[dt] = o[dt] * alpha;
;                     }
	v_cndmask_b32_e32 v204, v157, v209, vcc
	v_sub_f32_e32 v120, v157, v204
	v_exp_f32_e32 v132, v120
	s_nop 0
	v_pk_mul_f32 v[122:123], v[50:51], v[132:133] op_sel_hi:[1,0]
	v_pk_mul_f32 v[120:121], v[48:49], v[132:133] op_sel_hi:[1,0]
	v_pk_mul_f32 v[126:127], v[46:47], v[132:133] op_sel_hi:[1,0]
	v_pk_mul_f32 v[124:125], v[44:45], v[132:133] op_sel_hi:[1,0]
	v_pk_mul_f32 v[130:131], v[42:43], v[132:133] op_sel_hi:[1,0]
	v_pk_mul_f32 v[128:129], v[40:41], v[132:133] op_sel_hi:[1,0]
	v_pk_mul_f32 v[138:139], v[26:27], v[132:133] op_sel_hi:[1,0]
	v_pk_mul_f32 v[136:137], v[24:25], v[132:133] op_sel_hi:[1,0]
	v_pk_mul_f32 v[134:135], v[54:55], v[132:133] op_sel_hi:[1,0]
	v_pk_mul_f32 v[132:133], v[52:53], v[132:133] op_sel_hi:[1,0]
